# fold_pool inner loop: batch 18 loads per 8-j step with double buffering instead of a vmcnt(0) after every load (on top of v1)
# speedup vs baseline: 1.0144x; 1.0144x over previous
; __device__ __forceinline__ void fold_pool(int worker, int nworkers, int lane) {
;     ...
;     for (int w = worker; w < 1024; w += nworkers) {
;         const int k4 = __builtin_amdgcn_readfirstlane(w >> 3), ec = __builtin_amdgcn_readfirstlane(w & 7), kidx0 = k4 * 4, g = kidx0 >> 7;
;         const float* pr = pw + (size_t)kidx0 * 128; const float* sc = psc + g * 128; const float* wc = wo + (size_t)(g * 128) * D + ec * 256 + lane * 4;
;         f32x4 s[4];
; #pragma unroll
;         for (int i = 0; i < 4; ++i) s[i] = (f32x4){0.f, 0.f, 0.f, 0.f};
; #pragma unroll 8
;         for (int j = 0; j < 128; ++j) {
;             const f32x4 b = *(const f32x4*)(wc + (size_t)j * D) * sc[j];
; #pragma unroll
;             for (int i = 0; i < 4; ++i) s[i] = s[i] + b * pr[i * 128 + j];
;         }
.LBB0_740:
	v_readlane_b32 s6, v253, 1
	v_readlane_b32 s7, v253, 2
	s_nop 4
	s_load_dwordx2 s[24:25], s[6:7], 0x68
	s_ashr_i32 s9, s18, 1
	s_and_b32 s4, s9, -4
	s_and_b32 s22, s9, 0xffffff80
	s_ashr_i32 s5, s4, 31
	s_ashr_i32 s23, s22, 31
	s_lshl_b64 s[6:7], s[4:5], 9
	s_add_u32 s10, s56, s6
	s_addc_u32 s11, s57, s7
	s_lshl_b64 s[6:7], s[22:23], 13
	s_lshl_b64 s[22:23], s[22:23], 2
	s_add_u32 s22, s58, s22
	s_addc_u32 s23, s59, s23
	s_and_b32 s9, s18, 7
	s_lshl_b32 s9, s9, 10
	s_or_b32 s6, s6, s9
	s_waitcnt lgkmcnt(0)
	s_add_u32 s24, s24, s6
	s_addc_u32 s25, s25, s7
	v_lshlrev_b32_e32 v2, 4, v175
	v_mov_b32_e32 v28, 0
	v_mov_b32_e32 v29, 0
	v_mov_b32_e32 v26, 0
	v_mov_b32_e32 v27, 0
	v_mov_b32_e32 v30, 0
	v_mov_b32_e32 v31, 0
	v_mov_b32_e32 v10, 0
	v_mov_b32_e32 v11, 0
	v_mov_b32_e32 v32, 0
	v_mov_b32_e32 v33, 0
	v_mov_b32_e32 v14, 0
	v_mov_b32_e32 v15, 0
	v_mov_b32_e32 v34, 0
	v_mov_b32_e32 v35, 0
	v_mov_b32_e32 v18, 0
	v_mov_b32_e32 v19, 0
	s_mov_b32 s9, 0
	global_load_dwordx4 v[68:71], v2, s[24:25]
	s_add_u32 s24, s24, 0x2000
	s_addc_u32 s25, s25, 0
	global_load_dwordx4 v[72:75], v2, s[24:25]
	s_add_u32 s24, s24, 0x2000
	s_addc_u32 s25, s25, 0
	global_load_dwordx4 v[76:79], v2, s[24:25]
	s_add_u32 s24, s24, 0x2000
	s_addc_u32 s25, s25, 0
	global_load_dwordx4 v[80:83], v2, s[24:25]
	s_add_u32 s24, s24, 0x2000
	s_addc_u32 s25, s25, 0
	global_load_dwordx4 v[84:87], v2, s[24:25]
	s_add_u32 s24, s24, 0x2000
	s_addc_u32 s25, s25, 0
	global_load_dwordx4 v[88:91], v2, s[24:25]
	s_add_u32 s24, s24, 0x2000
	s_addc_u32 s25, s25, 0
	global_load_dwordx4 v[92:95], v2, s[24:25]
	s_add_u32 s24, s24, 0x2000
	s_addc_u32 s25, s25, 0
	global_load_dwordx4 v[96:99], v2, s[24:25]
	s_add_u32 s24, s24, 0x2000
	s_addc_u32 s25, s25, 0
	global_load_dwordx4 v[100:103], v1, s[22:23]
	global_load_dwordx4 v[104:107], v1, s[22:23] offset:16
	s_add_u32 s22, s22, 32
	s_addc_u32 s23, s23, 0
	global_load_dwordx4 v[108:111], v1, s[10:11] offset:0
	global_load_dwordx4 v[112:115], v1, s[10:11] offset:16
	global_load_dwordx4 v[116:119], v1, s[10:11] offset:512
	global_load_dwordx4 v[120:123], v1, s[10:11] offset:528
	global_load_dwordx4 v[124:127], v1, s[10:11] offset:1024
	global_load_dwordx4 v[128:131], v1, s[10:11] offset:1040
	global_load_dwordx4 v[132:135], v1, s[10:11] offset:1536
	global_load_dwordx4 v[136:139], v1, s[10:11] offset:1552
	s_add_u32 s10, s10, 32
	s_addc_u32 s11, s11, 0
.Lfp_loop:
	global_load_dwordx4 v[140:143], v2, s[24:25]
	s_add_u32 s24, s24, 0x2000
	s_addc_u32 s25, s25, 0
	global_load_dwordx4 v[144:147], v2, s[24:25]
	s_add_u32 s24, s24, 0x2000
	s_addc_u32 s25, s25, 0
	global_load_dwordx4 v[148:151], v2, s[24:25]
	s_add_u32 s24, s24, 0x2000
	s_addc_u32 s25, s25, 0
	global_load_dwordx4 v[152:155], v2, s[24:25]
	s_add_u32 s24, s24, 0x2000
	s_addc_u32 s25, s25, 0
	global_load_dwordx4 v[156:159], v2, s[24:25]
	s_add_u32 s24, s24, 0x2000
	s_addc_u32 s25, s25, 0
	global_load_dwordx4 v[160:163], v2, s[24:25]
	s_add_u32 s24, s24, 0x2000
	s_addc_u32 s25, s25, 0
	global_load_dwordx4 v[164:167], v2, s[24:25]
	s_add_u32 s24, s24, 0x2000
	s_addc_u32 s25, s25, 0
	global_load_dwordx4 v[188:191], v2, s[24:25]
	s_add_u32 s24, s24, 0x2000
	s_addc_u32 s25, s25, 0
	global_load_dwordx4 v[192:195], v1, s[22:23]
	global_load_dwordx4 v[196:199], v1, s[22:23] offset:16
	s_add_u32 s22, s22, 32
	s_addc_u32 s23, s23, 0
	global_load_dwordx4 v[200:203], v1, s[10:11] offset:0
	global_load_dwordx4 v[208:211], v1, s[10:11] offset:16
	global_load_dwordx4 v[40:43], v1, s[10:11] offset:512
	global_load_dwordx4 v[44:47], v1, s[10:11] offset:528
	global_load_dwordx4 v[48:51], v1, s[10:11] offset:1024
	global_load_dwordx4 v[52:55], v1, s[10:11] offset:1040
	global_load_dwordx4 v[56:59], v1, s[10:11] offset:1536
	global_load_dwordx4 v[64:67], v1, s[10:11] offset:1552
	s_add_u32 s10, s10, 32
	s_addc_u32 s11, s11, 0
	s_waitcnt vmcnt(18)
	v_pk_mul_f32 v[60:61], v[68:69], v[100:101] op_sel_hi:[1,0]
	v_pk_mul_f32 v[62:63], v[70:71], v[100:101] op_sel_hi:[1,0]
	v_pk_fma_f32 v[30:31], v[60:61], v[108:109], v[30:31] op_sel_hi:[1,0,1]
	v_pk_fma_f32 v[10:11], v[62:63], v[108:109], v[10:11] op_sel_hi:[1,0,1]
	v_pk_fma_f32 v[32:33], v[60:61], v[116:117], v[32:33] op_sel_hi:[1,0,1]
	v_pk_fma_f32 v[14:15], v[62:63], v[116:117], v[14:15] op_sel_hi:[1,0,1]
	v_pk_fma_f32 v[34:35], v[60:61], v[124:125], v[34:35] op_sel_hi:[1,0,1]
	v_pk_fma_f32 v[18:19], v[62:63], v[124:125], v[18:19] op_sel_hi:[1,0,1]
	v_pk_fma_f32 v[28:29], v[60:61], v[132:133], v[28:29] op_sel_hi:[1,0,1]
	v_pk_fma_f32 v[26:27], v[62:63], v[132:133], v[26:27] op_sel_hi:[1,0,1]
	v_pk_mul_f32 v[60:61], v[72:73], v[100:101] op_sel:[0,1]
	v_pk_mul_f32 v[62:63], v[74:75], v[100:101] op_sel:[0,1]
	v_pk_fma_f32 v[30:31], v[60:61], v[108:109], v[30:31] op_sel:[0,1,0]
	v_pk_fma_f32 v[10:11], v[62:63], v[108:109], v[10:11] op_sel:[0,1,0]
	v_pk_fma_f32 v[32:33], v[60:61], v[116:117], v[32:33] op_sel:[0,1,0]
	v_pk_fma_f32 v[14:15], v[62:63], v[116:117], v[14:15] op_sel:[0,1,0]
	v_pk_fma_f32 v[34:35], v[60:61], v[124:125], v[34:35] op_sel:[0,1,0]
	v_pk_fma_f32 v[18:19], v[62:63], v[124:125], v[18:19] op_sel:[0,1,0]
	v_pk_fma_f32 v[28:29], v[60:61], v[132:133], v[28:29] op_sel:[0,1,0]
	v_pk_fma_f32 v[26:27], v[62:63], v[132:133], v[26:27] op_sel:[0,1,0]
	v_pk_mul_f32 v[60:61], v[76:77], v[102:103] op_sel_hi:[1,0]
	v_pk_mul_f32 v[62:63], v[78:79], v[102:103] op_sel_hi:[1,0]
	v_pk_fma_f32 v[30:31], v[60:61], v[110:111], v[30:31] op_sel_hi:[1,0,1]
	v_pk_fma_f32 v[10:11], v[62:63], v[110:111], v[10:11] op_sel_hi:[1,0,1]
	v_pk_fma_f32 v[32:33], v[60:61], v[118:119], v[32:33] op_sel_hi:[1,0,1]
	v_pk_fma_f32 v[14:15], v[62:63], v[118:119], v[14:15] op_sel_hi:[1,0,1]
; __device__ __forceinline__ void fold_pool(int worker, int nworkers, int lane) {
;     ...
;         for (int j = 0; j < 128; ++j) {
;             const f32x4 b = *(const f32x4*)(wc + (size_t)j * D) * sc[j];
; #pragma unroll
;             for (int i = 0; i < 4; ++i) s[i] = s[i] + b * pr[i * 128 + j];
;         }
	v_pk_fma_f32 v[34:35], v[60:61], v[126:127], v[34:35] op_sel_hi:[1,0,1]
	v_pk_fma_f32 v[18:19], v[62:63], v[126:127], v[18:19] op_sel_hi:[1,0,1]
	v_pk_fma_f32 v[28:29], v[60:61], v[134:135], v[28:29] op_sel_hi:[1,0,1]
	v_pk_fma_f32 v[26:27], v[62:63], v[134:135], v[26:27] op_sel_hi:[1,0,1]
	v_pk_mul_f32 v[60:61], v[80:81], v[102:103] op_sel:[0,1]
	v_pk_mul_f32 v[62:63], v[82:83], v[102:103] op_sel:[0,1]
	v_pk_fma_f32 v[30:31], v[60:61], v[110:111], v[30:31] op_sel:[0,1,0]
	v_pk_fma_f32 v[10:11], v[62:63], v[110:111], v[10:11] op_sel:[0,1,0]
	v_pk_fma_f32 v[32:33], v[60:61], v[118:119], v[32:33] op_sel:[0,1,0]
	v_pk_fma_f32 v[14:15], v[62:63], v[118:119], v[14:15] op_sel:[0,1,0]
	v_pk_fma_f32 v[34:35], v[60:61], v[126:127], v[34:35] op_sel:[0,1,0]
	v_pk_fma_f32 v[18:19], v[62:63], v[126:127], v[18:19] op_sel:[0,1,0]
	v_pk_fma_f32 v[28:29], v[60:61], v[134:135], v[28:29] op_sel:[0,1,0]
	v_pk_fma_f32 v[26:27], v[62:63], v[134:135], v[26:27] op_sel:[0,1,0]
	v_pk_mul_f32 v[60:61], v[84:85], v[104:105] op_sel_hi:[1,0]
	v_pk_mul_f32 v[62:63], v[86:87], v[104:105] op_sel_hi:[1,0]
	v_pk_fma_f32 v[30:31], v[60:61], v[112:113], v[30:31] op_sel_hi:[1,0,1]
	v_pk_fma_f32 v[10:11], v[62:63], v[112:113], v[10:11] op_sel_hi:[1,0,1]
	v_pk_fma_f32 v[32:33], v[60:61], v[120:121], v[32:33] op_sel_hi:[1,0,1]
	v_pk_fma_f32 v[14:15], v[62:63], v[120:121], v[14:15] op_sel_hi:[1,0,1]
	v_pk_fma_f32 v[34:35], v[60:61], v[128:129], v[34:35] op_sel_hi:[1,0,1]
	v_pk_fma_f32 v[18:19], v[62:63], v[128:129], v[18:19] op_sel_hi:[1,0,1]
	v_pk_fma_f32 v[28:29], v[60:61], v[136:137], v[28:29] op_sel_hi:[1,0,1]
	v_pk_fma_f32 v[26:27], v[62:63], v[136:137], v[26:27] op_sel_hi:[1,0,1]
	v_pk_mul_f32 v[60:61], v[88:89], v[104:105] op_sel:[0,1]
	v_pk_mul_f32 v[62:63], v[90:91], v[104:105] op_sel:[0,1]
	v_pk_fma_f32 v[30:31], v[60:61], v[112:113], v[30:31] op_sel:[0,1,0]
	v_pk_fma_f32 v[10:11], v[62:63], v[112:113], v[10:11] op_sel:[0,1,0]
	v_pk_fma_f32 v[32:33], v[60:61], v[120:121], v[32:33] op_sel:[0,1,0]
	v_pk_fma_f32 v[14:15], v[62:63], v[120:121], v[14:15] op_sel:[0,1,0]
	v_pk_fma_f32 v[34:35], v[60:61], v[128:129], v[34:35] op_sel:[0,1,0]
	v_pk_fma_f32 v[18:19], v[62:63], v[128:129], v[18:19] op_sel:[0,1,0]
	v_pk_fma_f32 v[28:29], v[60:61], v[136:137], v[28:29] op_sel:[0,1,0]
	v_pk_fma_f32 v[26:27], v[62:63], v[136:137], v[26:27] op_sel:[0,1,0]
	v_pk_mul_f32 v[60:61], v[92:93], v[106:107] op_sel_hi:[1,0]
	v_pk_mul_f32 v[62:63], v[94:95], v[106:107] op_sel_hi:[1,0]
	v_pk_fma_f32 v[30:31], v[60:61], v[114:115], v[30:31] op_sel_hi:[1,0,1]
	v_pk_fma_f32 v[10:11], v[62:63], v[114:115], v[10:11] op_sel_hi:[1,0,1]
	v_pk_fma_f32 v[32:33], v[60:61], v[122:123], v[32:33] op_sel_hi:[1,0,1]
	v_pk_fma_f32 v[14:15], v[62:63], v[122:123], v[14:15] op_sel_hi:[1,0,1]
	v_pk_fma_f32 v[34:35], v[60:61], v[130:131], v[34:35] op_sel_hi:[1,0,1]
	v_pk_fma_f32 v[18:19], v[62:63], v[130:131], v[18:19] op_sel_hi:[1,0,1]
	v_pk_fma_f32 v[28:29], v[60:61], v[138:139], v[28:29] op_sel_hi:[1,0,1]
	v_pk_fma_f32 v[26:27], v[62:63], v[138:139], v[26:27] op_sel_hi:[1,0,1]
	v_pk_mul_f32 v[60:61], v[96:97], v[106:107] op_sel:[0,1]
	v_pk_mul_f32 v[62:63], v[98:99], v[106:107] op_sel:[0,1]
	v_pk_fma_f32 v[30:31], v[60:61], v[114:115], v[30:31] op_sel:[0,1,0]
	v_pk_fma_f32 v[10:11], v[62:63], v[114:115], v[10:11] op_sel:[0,1,0]
	v_pk_fma_f32 v[32:33], v[60:61], v[122:123], v[32:33] op_sel:[0,1,0]
	v_pk_fma_f32 v[14:15], v[62:63], v[122:123], v[14:15] op_sel:[0,1,0]
	v_pk_fma_f32 v[34:35], v[60:61], v[130:131], v[34:35] op_sel:[0,1,0]
	v_pk_fma_f32 v[18:19], v[62:63], v[130:131], v[18:19] op_sel:[0,1,0]
	v_pk_fma_f32 v[28:29], v[60:61], v[138:139], v[28:29] op_sel:[0,1,0]
	v_pk_fma_f32 v[26:27], v[62:63], v[138:139], v[26:27] op_sel:[0,1,0]
	s_cmp_eq_u32 s9, 14
	s_cbranch_scc1 .Lfp_lastb
	global_load_dwordx4 v[68:71], v2, s[24:25]
	s_add_u32 s24, s24, 0x2000
	s_addc_u32 s25, s25, 0
	global_load_dwordx4 v[72:75], v2, s[24:25]
	s_add_u32 s24, s24, 0x2000
	s_addc_u32 s25, s25, 0
	global_load_dwordx4 v[76:79], v2, s[24:25]
	s_add_u32 s24, s24, 0x2000
	s_addc_u32 s25, s25, 0
	global_load_dwordx4 v[80:83], v2, s[24:25]
	s_add_u32 s24, s24, 0x2000
	s_addc_u32 s25, s25, 0
	global_load_dwordx4 v[84:87], v2, s[24:25]
	s_add_u32 s24, s24, 0x2000
	s_addc_u32 s25, s25, 0
	global_load_dwordx4 v[88:91], v2, s[24:25]
	s_add_u32 s24, s24, 0x2000
	s_addc_u32 s25, s25, 0
	global_load_dwordx4 v[92:95], v2, s[24:25]
	s_add_u32 s24, s24, 0x2000
	s_addc_u32 s25, s25, 0
	global_load_dwordx4 v[96:99], v2, s[24:25]
	s_add_u32 s24, s24, 0x2000
	s_addc_u32 s25, s25, 0
	global_load_dwordx4 v[100:103], v1, s[22:23]
	global_load_dwordx4 v[104:107], v1, s[22:23] offset:16
	s_add_u32 s22, s22, 32
	s_addc_u32 s23, s23, 0
	global_load_dwordx4 v[108:111], v1, s[10:11] offset:0
	global_load_dwordx4 v[112:115], v1, s[10:11] offset:16
	global_load_dwordx4 v[116:119], v1, s[10:11] offset:512
	global_load_dwordx4 v[120:123], v1, s[10:11] offset:528
	global_load_dwordx4 v[124:127], v1, s[10:11] offset:1024
	global_load_dwordx4 v[128:131], v1, s[10:11] offset:1040
	global_load_dwordx4 v[132:135], v1, s[10:11] offset:1536
	global_load_dwordx4 v[136:139], v1, s[10:11] offset:1552
	s_add_u32 s10, s10, 32
	s_addc_u32 s11, s11, 0
	s_waitcnt vmcnt(18)
; __device__ __forceinline__ void fold_pool(int worker, int nworkers, int lane) {
;     ...
;         for (int j = 0; j < 128; ++j) {
;             const f32x4 b = *(const f32x4*)(wc + (size_t)j * D) * sc[j];
; #pragma unroll
;             for (int i = 0; i < 4; ++i) s[i] = s[i] + b * pr[i * 128 + j];
;         }
	v_pk_mul_f32 v[60:61], v[140:141], v[192:193] op_sel_hi:[1,0]
	v_pk_mul_f32 v[62:63], v[142:143], v[192:193] op_sel_hi:[1,0]
	v_pk_fma_f32 v[30:31], v[60:61], v[200:201], v[30:31] op_sel_hi:[1,0,1]
	v_pk_fma_f32 v[10:11], v[62:63], v[200:201], v[10:11] op_sel_hi:[1,0,1]
	v_pk_fma_f32 v[32:33], v[60:61], v[40:41], v[32:33] op_sel_hi:[1,0,1]
	v_pk_fma_f32 v[14:15], v[62:63], v[40:41], v[14:15] op_sel_hi:[1,0,1]
	v_pk_fma_f32 v[34:35], v[60:61], v[48:49], v[34:35] op_sel_hi:[1,0,1]
	v_pk_fma_f32 v[18:19], v[62:63], v[48:49], v[18:19] op_sel_hi:[1,0,1]
	v_pk_fma_f32 v[28:29], v[60:61], v[56:57], v[28:29] op_sel_hi:[1,0,1]
	v_pk_fma_f32 v[26:27], v[62:63], v[56:57], v[26:27] op_sel_hi:[1,0,1]
	v_pk_mul_f32 v[60:61], v[144:145], v[192:193] op_sel:[0,1]
	v_pk_mul_f32 v[62:63], v[146:147], v[192:193] op_sel:[0,1]
	v_pk_fma_f32 v[30:31], v[60:61], v[200:201], v[30:31] op_sel:[0,1,0]
	v_pk_fma_f32 v[10:11], v[62:63], v[200:201], v[10:11] op_sel:[0,1,0]
	v_pk_fma_f32 v[32:33], v[60:61], v[40:41], v[32:33] op_sel:[0,1,0]
	v_pk_fma_f32 v[14:15], v[62:63], v[40:41], v[14:15] op_sel:[0,1,0]
	v_pk_fma_f32 v[34:35], v[60:61], v[48:49], v[34:35] op_sel:[0,1,0]
	v_pk_fma_f32 v[18:19], v[62:63], v[48:49], v[18:19] op_sel:[0,1,0]
	v_pk_fma_f32 v[28:29], v[60:61], v[56:57], v[28:29] op_sel:[0,1,0]
	v_pk_fma_f32 v[26:27], v[62:63], v[56:57], v[26:27] op_sel:[0,1,0]
	v_pk_mul_f32 v[60:61], v[148:149], v[194:195] op_sel_hi:[1,0]
	v_pk_mul_f32 v[62:63], v[150:151], v[194:195] op_sel_hi:[1,0]
	v_pk_fma_f32 v[30:31], v[60:61], v[202:203], v[30:31] op_sel_hi:[1,0,1]
	v_pk_fma_f32 v[10:11], v[62:63], v[202:203], v[10:11] op_sel_hi:[1,0,1]
	v_pk_fma_f32 v[32:33], v[60:61], v[42:43], v[32:33] op_sel_hi:[1,0,1]
	v_pk_fma_f32 v[14:15], v[62:63], v[42:43], v[14:15] op_sel_hi:[1,0,1]
	v_pk_fma_f32 v[34:35], v[60:61], v[50:51], v[34:35] op_sel_hi:[1,0,1]
	v_pk_fma_f32 v[18:19], v[62:63], v[50:51], v[18:19] op_sel_hi:[1,0,1]
	v_pk_fma_f32 v[28:29], v[60:61], v[58:59], v[28:29] op_sel_hi:[1,0,1]
	v_pk_fma_f32 v[26:27], v[62:63], v[58:59], v[26:27] op_sel_hi:[1,0,1]
	v_pk_mul_f32 v[60:61], v[152:153], v[194:195] op_sel:[0,1]
	v_pk_mul_f32 v[62:63], v[154:155], v[194:195] op_sel:[0,1]
	v_pk_fma_f32 v[30:31], v[60:61], v[202:203], v[30:31] op_sel:[0,1,0]
	v_pk_fma_f32 v[10:11], v[62:63], v[202:203], v[10:11] op_sel:[0,1,0]
	v_pk_fma_f32 v[32:33], v[60:61], v[42:43], v[32:33] op_sel:[0,1,0]
	v_pk_fma_f32 v[14:15], v[62:63], v[42:43], v[14:15] op_sel:[0,1,0]
	v_pk_fma_f32 v[34:35], v[60:61], v[50:51], v[34:35] op_sel:[0,1,0]
	v_pk_fma_f32 v[18:19], v[62:63], v[50:51], v[18:19] op_sel:[0,1,0]
	v_pk_fma_f32 v[28:29], v[60:61], v[58:59], v[28:29] op_sel:[0,1,0]
	v_pk_fma_f32 v[26:27], v[62:63], v[58:59], v[26:27] op_sel:[0,1,0]
	v_pk_mul_f32 v[60:61], v[156:157], v[196:197] op_sel_hi:[1,0]
	v_pk_mul_f32 v[62:63], v[158:159], v[196:197] op_sel_hi:[1,0]
	v_pk_fma_f32 v[30:31], v[60:61], v[208:209], v[30:31] op_sel_hi:[1,0,1]
	v_pk_fma_f32 v[10:11], v[62:63], v[208:209], v[10:11] op_sel_hi:[1,0,1]
	v_pk_fma_f32 v[32:33], v[60:61], v[44:45], v[32:33] op_sel_hi:[1,0,1]
	v_pk_fma_f32 v[14:15], v[62:63], v[44:45], v[14:15] op_sel_hi:[1,0,1]
	v_pk_fma_f32 v[34:35], v[60:61], v[52:53], v[34:35] op_sel_hi:[1,0,1]
	v_pk_fma_f32 v[18:19], v[62:63], v[52:53], v[18:19] op_sel_hi:[1,0,1]
	v_pk_fma_f32 v[28:29], v[60:61], v[64:65], v[28:29] op_sel_hi:[1,0,1]
	v_pk_fma_f32 v[26:27], v[62:63], v[64:65], v[26:27] op_sel_hi:[1,0,1]
	v_pk_mul_f32 v[60:61], v[160:161], v[196:197] op_sel:[0,1]
	v_pk_mul_f32 v[62:63], v[162:163], v[196:197] op_sel:[0,1]
	v_pk_fma_f32 v[30:31], v[60:61], v[208:209], v[30:31] op_sel:[0,1,0]
	v_pk_fma_f32 v[10:11], v[62:63], v[208:209], v[10:11] op_sel:[0,1,0]
	v_pk_fma_f32 v[32:33], v[60:61], v[44:45], v[32:33] op_sel:[0,1,0]
	v_pk_fma_f32 v[14:15], v[62:63], v[44:45], v[14:15] op_sel:[0,1,0]
	v_pk_fma_f32 v[34:35], v[60:61], v[52:53], v[34:35] op_sel:[0,1,0]
	v_pk_fma_f32 v[18:19], v[62:63], v[52:53], v[18:19] op_sel:[0,1,0]
	v_pk_fma_f32 v[28:29], v[60:61], v[64:65], v[28:29] op_sel:[0,1,0]
	v_pk_fma_f32 v[26:27], v[62:63], v[64:65], v[26:27] op_sel:[0,1,0]
	v_pk_mul_f32 v[60:61], v[164:165], v[198:199] op_sel_hi:[1,0]
	v_pk_mul_f32 v[62:63], v[166:167], v[198:199] op_sel_hi:[1,0]
	v_pk_fma_f32 v[30:31], v[60:61], v[210:211], v[30:31] op_sel_hi:[1,0,1]
	v_pk_fma_f32 v[10:11], v[62:63], v[210:211], v[10:11] op_sel_hi:[1,0,1]
	v_pk_fma_f32 v[32:33], v[60:61], v[46:47], v[32:33] op_sel_hi:[1,0,1]
	v_pk_fma_f32 v[14:15], v[62:63], v[46:47], v[14:15] op_sel_hi:[1,0,1]
	v_pk_fma_f32 v[34:35], v[60:61], v[54:55], v[34:35] op_sel_hi:[1,0,1]
	v_pk_fma_f32 v[18:19], v[62:63], v[54:55], v[18:19] op_sel_hi:[1,0,1]
	v_pk_fma_f32 v[28:29], v[60:61], v[66:67], v[28:29] op_sel_hi:[1,0,1]
	v_pk_fma_f32 v[26:27], v[62:63], v[66:67], v[26:27] op_sel_hi:[1,0,1]
	v_pk_mul_f32 v[60:61], v[188:189], v[198:199] op_sel:[0,1]
	v_pk_mul_f32 v[62:63], v[190:191], v[198:199] op_sel:[0,1]
	v_pk_fma_f32 v[30:31], v[60:61], v[210:211], v[30:31] op_sel:[0,1,0]
	v_pk_fma_f32 v[10:11], v[62:63], v[210:211], v[10:11] op_sel:[0,1,0]
	v_pk_fma_f32 v[32:33], v[60:61], v[46:47], v[32:33] op_sel:[0,1,0]
	v_pk_fma_f32 v[14:15], v[62:63], v[46:47], v[14:15] op_sel:[0,1,0]
	v_pk_fma_f32 v[34:35], v[60:61], v[54:55], v[34:35] op_sel:[0,1,0]
	v_pk_fma_f32 v[18:19], v[62:63], v[54:55], v[18:19] op_sel:[0,1,0]
	v_pk_fma_f32 v[28:29], v[60:61], v[66:67], v[28:29] op_sel:[0,1,0]
	v_pk_fma_f32 v[26:27], v[62:63], v[66:67], v[26:27] op_sel:[0,1,0]
	s_add_u32 s9, s9, 2
	s_branch .Lfp_loop
; __device__ __forceinline__ unsigned cvt_pk_bf16(float lo, float hi) { unsigned r; asm volatile("v_cvt_pk_bf16_f32 %0, %1, %2" : "=v"(r) : "v"(lo), "v"(hi)); return r; }
; __device__ __forceinline__ void fold_pool(int worker, int nworkers, int lane) {
;     ...
;         for (int j = 0; j < 128; ++j) {
;             const f32x4 b = *(const f32x4*)(wc + (size_t)j * D) * sc[j];
; #pragma unroll
;             for (int i = 0; i < 4; ++i) s[i] = s[i] + b * pr[i * 128 + j];
;         }
; #pragma unroll
;         for (int e = 0; e < 4; ++e) {
;             u32x2 o; o.x = cvt_pk_bf16(s[0][e], s[1][e]); o.y = cvt_pk_bf16(s[2][e], s[3][e]);
;             *(u32x2*)(Woe + (size_t)(ec * 256 + lane * 4 + e) * 1024 + kidx0) = o;
;         }
.Lfp_lastb:
	s_waitcnt vmcnt(0)
	v_pk_mul_f32 v[60:61], v[140:141], v[192:193] op_sel_hi:[1,0]
	v_pk_mul_f32 v[62:63], v[142:143], v[192:193] op_sel_hi:[1,0]
	v_pk_fma_f32 v[30:31], v[60:61], v[200:201], v[30:31] op_sel_hi:[1,0,1]
	v_pk_fma_f32 v[10:11], v[62:63], v[200:201], v[10:11] op_sel_hi:[1,0,1]
	v_pk_fma_f32 v[32:33], v[60:61], v[40:41], v[32:33] op_sel_hi:[1,0,1]
	v_pk_fma_f32 v[14:15], v[62:63], v[40:41], v[14:15] op_sel_hi:[1,0,1]
	v_pk_fma_f32 v[34:35], v[60:61], v[48:49], v[34:35] op_sel_hi:[1,0,1]
	v_pk_fma_f32 v[18:19], v[62:63], v[48:49], v[18:19] op_sel_hi:[1,0,1]
	v_pk_fma_f32 v[28:29], v[60:61], v[56:57], v[28:29] op_sel_hi:[1,0,1]
	v_pk_fma_f32 v[26:27], v[62:63], v[56:57], v[26:27] op_sel_hi:[1,0,1]
	v_pk_mul_f32 v[60:61], v[144:145], v[192:193] op_sel:[0,1]
	v_pk_mul_f32 v[62:63], v[146:147], v[192:193] op_sel:[0,1]
	v_pk_fma_f32 v[30:31], v[60:61], v[200:201], v[30:31] op_sel:[0,1,0]
	v_pk_fma_f32 v[10:11], v[62:63], v[200:201], v[10:11] op_sel:[0,1,0]
	v_pk_fma_f32 v[32:33], v[60:61], v[40:41], v[32:33] op_sel:[0,1,0]
	v_pk_fma_f32 v[14:15], v[62:63], v[40:41], v[14:15] op_sel:[0,1,0]
	v_pk_fma_f32 v[34:35], v[60:61], v[48:49], v[34:35] op_sel:[0,1,0]
	v_pk_fma_f32 v[18:19], v[62:63], v[48:49], v[18:19] op_sel:[0,1,0]
	v_pk_fma_f32 v[28:29], v[60:61], v[56:57], v[28:29] op_sel:[0,1,0]
	v_pk_fma_f32 v[26:27], v[62:63], v[56:57], v[26:27] op_sel:[0,1,0]
	v_pk_mul_f32 v[60:61], v[148:149], v[194:195] op_sel_hi:[1,0]
	v_pk_mul_f32 v[62:63], v[150:151], v[194:195] op_sel_hi:[1,0]
	v_pk_fma_f32 v[30:31], v[60:61], v[202:203], v[30:31] op_sel_hi:[1,0,1]
	v_pk_fma_f32 v[10:11], v[62:63], v[202:203], v[10:11] op_sel_hi:[1,0,1]
	v_pk_fma_f32 v[32:33], v[60:61], v[42:43], v[32:33] op_sel_hi:[1,0,1]
	v_pk_fma_f32 v[14:15], v[62:63], v[42:43], v[14:15] op_sel_hi:[1,0,1]
	v_pk_fma_f32 v[34:35], v[60:61], v[50:51], v[34:35] op_sel_hi:[1,0,1]
	v_pk_fma_f32 v[18:19], v[62:63], v[50:51], v[18:19] op_sel_hi:[1,0,1]
	v_pk_fma_f32 v[28:29], v[60:61], v[58:59], v[28:29] op_sel_hi:[1,0,1]
	v_pk_fma_f32 v[26:27], v[62:63], v[58:59], v[26:27] op_sel_hi:[1,0,1]
	v_pk_mul_f32 v[60:61], v[152:153], v[194:195] op_sel:[0,1]
	v_pk_mul_f32 v[62:63], v[154:155], v[194:195] op_sel:[0,1]
	v_pk_fma_f32 v[30:31], v[60:61], v[202:203], v[30:31] op_sel:[0,1,0]
	v_pk_fma_f32 v[10:11], v[62:63], v[202:203], v[10:11] op_sel:[0,1,0]
	v_pk_fma_f32 v[32:33], v[60:61], v[42:43], v[32:33] op_sel:[0,1,0]
	v_pk_fma_f32 v[14:15], v[62:63], v[42:43], v[14:15] op_sel:[0,1,0]
	v_pk_fma_f32 v[34:35], v[60:61], v[50:51], v[34:35] op_sel:[0,1,0]
	v_pk_fma_f32 v[18:19], v[62:63], v[50:51], v[18:19] op_sel:[0,1,0]
	v_pk_fma_f32 v[28:29], v[60:61], v[58:59], v[28:29] op_sel:[0,1,0]
	v_pk_fma_f32 v[26:27], v[62:63], v[58:59], v[26:27] op_sel:[0,1,0]
	v_pk_mul_f32 v[60:61], v[156:157], v[196:197] op_sel_hi:[1,0]
	v_pk_mul_f32 v[62:63], v[158:159], v[196:197] op_sel_hi:[1,0]
	v_pk_fma_f32 v[30:31], v[60:61], v[208:209], v[30:31] op_sel_hi:[1,0,1]
	v_pk_fma_f32 v[10:11], v[62:63], v[208:209], v[10:11] op_sel_hi:[1,0,1]
	v_pk_fma_f32 v[32:33], v[60:61], v[44:45], v[32:33] op_sel_hi:[1,0,1]
	v_pk_fma_f32 v[14:15], v[62:63], v[44:45], v[14:15] op_sel_hi:[1,0,1]
	v_pk_fma_f32 v[34:35], v[60:61], v[52:53], v[34:35] op_sel_hi:[1,0,1]
	v_pk_fma_f32 v[18:19], v[62:63], v[52:53], v[18:19] op_sel_hi:[1,0,1]
	v_pk_fma_f32 v[28:29], v[60:61], v[64:65], v[28:29] op_sel_hi:[1,0,1]
	v_pk_fma_f32 v[26:27], v[62:63], v[64:65], v[26:27] op_sel_hi:[1,0,1]
	v_pk_mul_f32 v[60:61], v[160:161], v[196:197] op_sel:[0,1]
	v_pk_mul_f32 v[62:63], v[162:163], v[196:197] op_sel:[0,1]
	v_pk_fma_f32 v[30:31], v[60:61], v[208:209], v[30:31] op_sel:[0,1,0]
	v_pk_fma_f32 v[10:11], v[62:63], v[208:209], v[10:11] op_sel:[0,1,0]
	v_pk_fma_f32 v[32:33], v[60:61], v[44:45], v[32:33] op_sel:[0,1,0]
	v_pk_fma_f32 v[14:15], v[62:63], v[44:45], v[14:15] op_sel:[0,1,0]
	v_pk_fma_f32 v[34:35], v[60:61], v[52:53], v[34:35] op_sel:[0,1,0]
	v_pk_fma_f32 v[18:19], v[62:63], v[52:53], v[18:19] op_sel:[0,1,0]
	v_pk_fma_f32 v[28:29], v[60:61], v[64:65], v[28:29] op_sel:[0,1,0]
	v_pk_fma_f32 v[26:27], v[62:63], v[64:65], v[26:27] op_sel:[0,1,0]
	v_pk_mul_f32 v[60:61], v[164:165], v[198:199] op_sel_hi:[1,0]
	v_pk_mul_f32 v[62:63], v[166:167], v[198:199] op_sel_hi:[1,0]
	v_pk_fma_f32 v[30:31], v[60:61], v[210:211], v[30:31] op_sel_hi:[1,0,1]
	v_pk_fma_f32 v[10:11], v[62:63], v[210:211], v[10:11] op_sel_hi:[1,0,1]
	v_pk_fma_f32 v[32:33], v[60:61], v[46:47], v[32:33] op_sel_hi:[1,0,1]
	v_pk_fma_f32 v[14:15], v[62:63], v[46:47], v[14:15] op_sel_hi:[1,0,1]
	v_pk_fma_f32 v[34:35], v[60:61], v[54:55], v[34:35] op_sel_hi:[1,0,1]
	v_pk_fma_f32 v[18:19], v[62:63], v[54:55], v[18:19] op_sel_hi:[1,0,1]
	v_pk_fma_f32 v[28:29], v[60:61], v[66:67], v[28:29] op_sel_hi:[1,0,1]
	v_pk_fma_f32 v[26:27], v[62:63], v[66:67], v[26:27] op_sel_hi:[1,0,1]
	v_pk_mul_f32 v[60:61], v[188:189], v[198:199] op_sel:[0,1]
	v_pk_mul_f32 v[62:63], v[190:191], v[198:199] op_sel:[0,1]
	v_pk_fma_f32 v[30:31], v[60:61], v[210:211], v[30:31] op_sel:[0,1,0]
	v_pk_fma_f32 v[10:11], v[62:63], v[210:211], v[10:11] op_sel:[0,1,0]
	v_pk_fma_f32 v[32:33], v[60:61], v[46:47], v[32:33] op_sel:[0,1,0]
	v_pk_fma_f32 v[14:15], v[62:63], v[46:47], v[14:15] op_sel:[0,1,0]
	v_pk_fma_f32 v[34:35], v[60:61], v[54:55], v[34:35] op_sel:[0,1,0]
	v_pk_fma_f32 v[18:19], v[62:63], v[54:55], v[18:19] op_sel:[0,1,0]
	v_pk_fma_f32 v[28:29], v[60:61], v[66:67], v[28:29] op_sel:[0,1,0]
	v_pk_fma_f32 v[26:27], v[62:63], v[66:67], v[26:27] op_sel:[0,1,0]
	s_lshl_b32 s6, s18, 8
	s_and_b32 s6, s6, 0x700
	s_lshl_b64 s[4:5], s[4:5], 1
	s_add_u32 s4, s2, s4
	v_or_b32_e32 v0, s6, v36
	s_addc_u32 s5, s8, s5
	v_lshlrev_b32_e32 v0, 11, v0
	v_cvt_pk_bf16_f32 v2, v30, v32
	v_cvt_pk_bf16_f32 v3, v34, v28
	v_lshl_add_u64 v[4:5], s[4:5], 0, v[0:1]
	global_store_dwordx2 v0, v[2:3], s[4:5]
	v_cvt_pk_bf16_f32 v2, v31, v33
	v_cvt_pk_bf16_f32 v3, v35, v29
	global_store_dwordx2 v0, v[2:3], s[4:5] offset:2048
	v_add_co_u32_e32 v4, vcc, s3, v4
	s_add_i32 s4, s18, 0x400
	v_cvt_pk_bf16_f32 v2, v10, v14
	v_cvt_pk_bf16_f32 v3, v18, v26
	s_nop 0
	v_addc_co_u32_e32 v5, vcc, 0, v5, vcc
	s_cmp_gt_i32 s18, -1
	s_mov_b32 s18, s4
	global_store_dwordx2 v[4:5], v[2:3], off
	v_cvt_pk_bf16_f32 v2, v11, v15
	v_cvt_pk_bf16_f32 v3, v19, v27
	global_store_dwordx2 v[4:5], v[2:3], off offset:2048
	s_cbranch_scc0 .LBB0_740
